# SwiGLU epilogue: adjacent per-value sigmoid chains interleaved pairwise (breaks the 64-deep serial exp/rcp dependency chain, drops the hazard nops)
# speedup vs baseline: 1.0010x; 1.0003x over previous
; __device__ __forceinline__ unsigned cvt_pk_bf16(float lo, float hi) { unsigned r; asm volatile("v_cvt_pk_bf16_f32 %0, %1, %2" : "=v"(r) : "v"(lo), "v"(hi)); return r; }
; __device__ __forceinline__ float sigmoid_f(float x) { return __builtin_amdgcn_rcpf(1.0f + __builtin_amdgcn_exp2f(-1.4426950408889634f * x)); }
;     __device__ __forceinline__ void operator()(const f32x4 (&acc)[2][2][4][2], const Unit& u, int wr, int wc, int fr, int fq) const {
;         const int row0 = u.pm * BM + wr * 64 + fr, col0 = u.pn * HALF + wc * 32 + 8 * fq;
; #pragma unroll
;         for (int ai = 0; ai < 2; ++ai)
; #pragma unroll
;             for (int m = 0; m < 4; ++m) {
;                 bf16_t* rowp = O + (size_t)(row0 + ai * HALF + m * 16) * ldc + col0;
;                 float v[8];
; #pragma unroll
;                 for (int n = 0; n < 2; ++n)
; #pragma unroll
;                     for (int e = 0; e < 4; ++e) { const float g = acc[ai][0][m][n][e], up = acc[ai][1][m][n][e]; v[4 * n + e] = g * sigmoid_f(g) * up; }
;                 u32x4 w; w.x = cvt_pk_bf16(v[0], v[1]); w.y = cvt_pk_bf16(v[2], v[3]); w.z = cvt_pk_bf16(v[4], v[5]); w.w = cvt_pk_bf16(v[6], v[7]);
;                 *(u32x4*)rowp = w;
;             }
.LBB0_511:
	v_mul_f32_e32 v147, 0xbfb8aa3b, v126
	v_exp_f32_e32 v147, v147
	v_lshl_or_b32 v148, s3, 7, v144
	v_lshl_add_u32 v146, s34, 8, v142
	v_ashrrev_i32_e32 v149, 31, v148
	v_add_f32_e32 v147, 1.0, v147
	v_rcp_f32_e32 v147, v147
	v_mov_b64_e32 v[140:141], s[78:79]
	v_mad_i64_i32 v[150:151], s[18:19], v146, s89, v[140:141]
	v_mul_f32_e32 v126, v126, v147
	v_mul_f32_e32 v122, v126, v122
	v_mul_f32_e32 v126, 0xbfb8aa3b, v127
	v_exp_f32_e32 v126, v126
	s_mov_b64 s[34:35], -1
	s_andn2_b64 vcc, exec, s[6:7]
	v_add_f32_e32 v126, 1.0, v126
	v_rcp_f32_e32 v126, v126
	s_nop 0
	v_mul_f32_e32 v126, v127, v126
	v_mul_f32_e32 v123, v126, v123
	v_mul_f32_e32 v126, 0xbfb8aa3b, v128
	v_mul_f32_e32 v250, 0xbfb8aa3b, v129
	v_exp_f32_e32 v126, v126
	v_exp_f32_e32 v250, v250
	v_add_f32_e32 v126, 1.0, v126
	v_add_f32_e32 v250, 1.0, v250
	v_rcp_f32_e32 v126, v126
	v_rcp_f32_e32 v250, v250
	v_mul_f32_e32 v126, v128, v126
	v_mul_f32_e32 v250, v129, v250
	v_mul_f32_e32 v124, v126, v124
	v_mul_f32_e32 v125, v250, v125
	v_mul_f32_e32 v126, 0xbfb8aa3b, v118
	v_mul_f32_e32 v250, 0xbfb8aa3b, v119
	v_exp_f32_e32 v126, v126
	v_exp_f32_e32 v250, v250
	v_add_f32_e32 v126, 1.0, v126
	v_add_f32_e32 v250, 1.0, v250
	v_rcp_f32_e32 v126, v126
	v_rcp_f32_e32 v250, v250
	v_mul_f32_e32 v118, v118, v126
	v_mul_f32_e32 v250, v119, v250
	v_mul_f32_e32 v118, v118, v114
	v_mul_f32_e32 v119, v250, v115
	v_mul_f32_e32 v114, 0xbfb8aa3b, v120
	v_exp_f32_e32 v114, v114
	s_nop 0
	v_add_f32_e32 v114, 1.0, v114
	v_rcp_f32_e32 v114, v114
	s_nop 0
	v_mul_f32_e32 v114, v120, v114
	v_mul_f32_e32 v126, v114, v116
	v_mul_f32_e32 v114, 0xbfb8aa3b, v121
	v_exp_f32_e32 v114, v114
	v_cvt_pk_bf16_f32 v116, v122, v123
	s_nop 0
	v_add_f32_e32 v114, 1.0, v114
	v_rcp_f32_e32 v114, v114
	s_nop 0
	v_mul_f32_e32 v114, v121, v114
	v_mul_f32_e32 v127, v114, v117
	v_lshlrev_b64 v[114:115], 1, v[148:149]
	v_lshl_add_u64 v[120:121], v[150:151], 0, v[114:115]
	v_cvt_pk_bf16_f32 v117, v124, v125
	v_cvt_pk_bf16_f32 v118, v118, v119
	v_cvt_pk_bf16_f32 v119, v126, v127
	global_store_dwordx4 v[120:121], v[116:119], off
	s_nop 1
	v_mul_f32_e32 v118, 0xbfb8aa3b, v110
	v_exp_f32_e32 v118, v118
	v_or_b32_e32 v116, 16, v146
	v_mad_i64_i32 v[116:117], s[18:19], v116, s89, v[140:141]
	v_add_f32_e32 v118, 1.0, v118
	v_rcp_f32_e32 v118, v118
	s_nop 0
	v_mul_f32_e32 v110, v110, v118
	v_mul_f32_e32 v106, v110, v106
	v_mul_f32_e32 v110, 0xbfb8aa3b, v111
	v_mul_f32_e32 v250, 0xbfb8aa3b, v112
	v_exp_f32_e32 v110, v110
	v_exp_f32_e32 v250, v250
	v_add_f32_e32 v110, 1.0, v110
	v_add_f32_e32 v250, 1.0, v250
	v_rcp_f32_e32 v110, v110
	v_rcp_f32_e32 v250, v250
	v_mul_f32_e32 v110, v111, v110
	v_mul_f32_e32 v250, v112, v250
	v_mul_f32_e32 v107, v110, v107
	v_mul_f32_e32 v108, v250, v108
	v_mul_f32_e32 v110, 0xbfb8aa3b, v113
	v_exp_f32_e32 v110, v110
	s_nop 0
	v_add_f32_e32 v110, 1.0, v110
	v_rcp_f32_e32 v110, v110
	s_nop 0
	v_mul_f32_e32 v110, v113, v110
	v_mul_f32_e32 v109, v110, v109
	v_mul_f32_e32 v110, 0xbfb8aa3b, v102
	v_mul_f32_e32 v250, 0xbfb8aa3b, v103
	v_exp_f32_e32 v110, v110
	v_exp_f32_e32 v250, v250
	v_add_f32_e32 v110, 1.0, v110
	v_add_f32_e32 v250, 1.0, v250
	v_rcp_f32_e32 v110, v110
	v_rcp_f32_e32 v250, v250
	v_mul_f32_e32 v102, v102, v110
	v_mul_f32_e32 v250, v103, v250
	v_mul_f32_e32 v110, v102, v98
	v_mul_f32_e32 v111, v250, v99
	v_mul_f32_e32 v98, 0xbfb8aa3b, v104
	v_exp_f32_e32 v98, v98
	v_lshl_add_u64 v[102:103], v[116:117], 0, v[114:115]
	v_add_f32_e32 v98, 1.0, v98
	v_rcp_f32_e32 v98, v98
	s_nop 0
	v_mul_f32_e32 v98, v104, v98
	v_mul_f32_e32 v104, v98, v100
	v_mul_f32_e32 v98, 0xbfb8aa3b, v105
	v_exp_f32_e32 v98, v98
	s_nop 0
	v_add_f32_e32 v98, 1.0, v98
	v_rcp_f32_e32 v98, v98
	s_nop 0
	v_mul_f32_e32 v98, v105, v98
	v_mul_f32_e32 v101, v98, v101
	v_cvt_pk_bf16_f32 v98, v106, v107
	v_cvt_pk_bf16_f32 v99, v108, v109
	v_cvt_pk_bf16_f32 v100, v110, v111
	v_cvt_pk_bf16_f32 v101, v104, v101
	global_store_dwordx4 v[102:103], v[98:101], off
	s_nop 1
	v_mul_f32_e32 v100, 0xbfb8aa3b, v94
	v_exp_f32_e32 v100, v100
	v_or_b32_e32 v98, 32, v146
	v_mad_i64_i32 v[98:99], s[18:19], v98, s89, v[140:141]
	v_add_f32_e32 v100, 1.0, v100
	v_rcp_f32_e32 v100, v100
	s_nop 0
	v_mul_f32_e32 v94, v94, v100
	v_mul_f32_e32 v90, v94, v90
	v_mul_f32_e32 v94, 0xbfb8aa3b, v95
	v_mul_f32_e32 v250, 0xbfb8aa3b, v96
	v_exp_f32_e32 v94, v94
	v_exp_f32_e32 v250, v250
	v_add_f32_e32 v94, 1.0, v94
	v_add_f32_e32 v250, 1.0, v250
	v_rcp_f32_e32 v94, v94
	v_rcp_f32_e32 v250, v250
	v_mul_f32_e32 v94, v95, v94
	v_mul_f32_e32 v250, v96, v250
	v_mul_f32_e32 v91, v94, v91
	v_mul_f32_e32 v92, v250, v92
	v_mul_f32_e32 v94, 0xbfb8aa3b, v97
	v_exp_f32_e32 v94, v94
	s_nop 0
	v_add_f32_e32 v94, 1.0, v94
	v_rcp_f32_e32 v94, v94
	s_nop 0
	v_mul_f32_e32 v94, v97, v94
	v_mul_f32_e32 v93, v94, v93
	v_mul_f32_e32 v94, 0xbfb8aa3b, v86
	v_mul_f32_e32 v250, 0xbfb8aa3b, v87
	v_exp_f32_e32 v94, v94
	v_exp_f32_e32 v250, v250
	v_add_f32_e32 v94, 1.0, v94
	v_add_f32_e32 v250, 1.0, v250
	v_rcp_f32_e32 v94, v94
	v_rcp_f32_e32 v250, v250
	v_mul_f32_e32 v86, v86, v94
	v_mul_f32_e32 v250, v87, v250
	v_mul_f32_e32 v94, v86, v82
	v_mul_f32_e32 v95, v250, v83
	v_mul_f32_e32 v82, 0xbfb8aa3b, v88
	v_exp_f32_e32 v82, v82
	v_lshl_add_u64 v[86:87], v[98:99], 0, v[114:115]
	v_add_f32_e32 v82, 1.0, v82
	v_rcp_f32_e32 v82, v82
	s_nop 0
	v_mul_f32_e32 v82, v88, v82
	v_mul_f32_e32 v88, v82, v84
	v_mul_f32_e32 v82, 0xbfb8aa3b, v89
	v_exp_f32_e32 v82, v82
	s_nop 0
	v_add_f32_e32 v82, 1.0, v82
	v_rcp_f32_e32 v82, v82
	s_nop 0
	v_mul_f32_e32 v82, v89, v82
	v_mul_f32_e32 v85, v82, v85
	v_cvt_pk_bf16_f32 v82, v90, v91
	v_cvt_pk_bf16_f32 v83, v92, v93
	v_cvt_pk_bf16_f32 v84, v94, v95
	v_cvt_pk_bf16_f32 v85, v88, v85
; __device__ __forceinline__ unsigned cvt_pk_bf16(float lo, float hi) { unsigned r; asm volatile("v_cvt_pk_bf16_f32 %0, %1, %2" : "=v"(r) : "v"(lo), "v"(hi)); return r; }
; __device__ __forceinline__ float sigmoid_f(float x) { return __builtin_amdgcn_rcpf(1.0f + __builtin_amdgcn_exp2f(-1.4426950408889634f * x)); }
;     __device__ __forceinline__ void operator()(const f32x4 (&acc)[2][2][4][2], const Unit& u, int wr, int wc, int fr, int fq) const {
;         const int row0 = u.pm * BM + wr * 64 + fr, col0 = u.pn * HALF + wc * 32 + 8 * fq;
; #pragma unroll
;         for (int ai = 0; ai < 2; ++ai)
; #pragma unroll
;             for (int m = 0; m < 4; ++m) {
;                 bf16_t* rowp = O + (size_t)(row0 + ai * HALF + m * 16) * ldc + col0;
;                 float v[8];
; #pragma unroll
;                 for (int n = 0; n < 2; ++n)
; #pragma unroll
;                     for (int e = 0; e < 4; ++e) { const float g = acc[ai][0][m][n][e], up = acc[ai][1][m][n][e]; v[4 * n + e] = g * sigmoid_f(g) * up; }
;                 u32x4 w; w.x = cvt_pk_bf16(v[0], v[1]); w.y = cvt_pk_bf16(v[2], v[3]); w.z = cvt_pk_bf16(v[4], v[5]); w.w = cvt_pk_bf16(v[6], v[7]);
;                 *(u32x4*)rowp = w;
;             }
	global_store_dwordx4 v[86:87], v[82:85], off
	s_nop 1
	v_mul_f32_e32 v84, 0xbfb8aa3b, v78
	v_exp_f32_e32 v84, v84
	v_or_b32_e32 v82, 48, v146
	v_mad_i64_i32 v[82:83], s[18:19], v82, s89, v[140:141]
	v_add_f32_e32 v84, 1.0, v84
	v_rcp_f32_e32 v84, v84
	s_nop 0
	v_mul_f32_e32 v78, v78, v84
	v_mul_f32_e32 v74, v78, v74
	v_mul_f32_e32 v78, 0xbfb8aa3b, v79
	v_mul_f32_e32 v250, 0xbfb8aa3b, v80
	v_exp_f32_e32 v78, v78
	v_exp_f32_e32 v250, v250
	v_add_f32_e32 v78, 1.0, v78
	v_add_f32_e32 v250, 1.0, v250
	v_rcp_f32_e32 v78, v78
	v_rcp_f32_e32 v250, v250
	v_mul_f32_e32 v78, v79, v78
	v_mul_f32_e32 v250, v80, v250
	v_mul_f32_e32 v75, v78, v75
	v_mul_f32_e32 v76, v250, v76
	v_mul_f32_e32 v78, 0xbfb8aa3b, v81
	v_exp_f32_e32 v78, v78
	s_nop 0
	v_add_f32_e32 v78, 1.0, v78
	v_rcp_f32_e32 v78, v78
	s_nop 0
	v_mul_f32_e32 v78, v81, v78
	v_mul_f32_e32 v77, v78, v77
	v_mul_f32_e32 v78, 0xbfb8aa3b, v70
	v_mul_f32_e32 v250, 0xbfb8aa3b, v71
	v_exp_f32_e32 v78, v78
	v_exp_f32_e32 v250, v250
	v_add_f32_e32 v78, 1.0, v78
	v_add_f32_e32 v250, 1.0, v250
	v_rcp_f32_e32 v78, v78
	v_rcp_f32_e32 v250, v250
	v_mul_f32_e32 v70, v70, v78
	v_mul_f32_e32 v250, v71, v250
	v_mul_f32_e32 v78, v70, v66
	v_mul_f32_e32 v79, v250, v67
	v_mul_f32_e32 v66, 0xbfb8aa3b, v72
	v_exp_f32_e32 v66, v66
	v_lshl_add_u64 v[70:71], v[82:83], 0, v[114:115]
	v_add_f32_e32 v66, 1.0, v66
	v_rcp_f32_e32 v66, v66
	s_nop 0
	v_mul_f32_e32 v66, v72, v66
	v_mul_f32_e32 v72, v66, v68
	v_mul_f32_e32 v66, 0xbfb8aa3b, v73
	v_exp_f32_e32 v66, v66
	s_nop 0
	v_add_f32_e32 v66, 1.0, v66
	v_rcp_f32_e32 v66, v66
	s_nop 0
	v_mul_f32_e32 v66, v73, v66
	v_mul_f32_e32 v69, v66, v69
	v_cvt_pk_bf16_f32 v66, v74, v75
	v_cvt_pk_bf16_f32 v67, v76, v77
	v_cvt_pk_bf16_f32 v68, v78, v79
	v_cvt_pk_bf16_f32 v69, v72, v69
	global_store_dwordx4 v[70:71], v[66:69], off
	s_nop 1
	v_mul_f32_e32 v68, 0xbfb8aa3b, v62
	v_exp_f32_e32 v68, v68
	v_add_u32_e32 v66, 0x80, v146
	v_mad_i64_i32 v[66:67], s[18:19], v66, s89, v[140:141]
	v_add_f32_e32 v68, 1.0, v68
	v_rcp_f32_e32 v68, v68
	s_nop 0
	v_mul_f32_e32 v62, v62, v68
	v_mul_f32_e32 v58, v62, v58
	v_mul_f32_e32 v62, 0xbfb8aa3b, v63
	v_mul_f32_e32 v250, 0xbfb8aa3b, v64
	v_exp_f32_e32 v62, v62
	v_exp_f32_e32 v250, v250
	v_add_f32_e32 v62, 1.0, v62
	v_add_f32_e32 v250, 1.0, v250
	v_rcp_f32_e32 v62, v62
	v_rcp_f32_e32 v250, v250
	v_mul_f32_e32 v62, v63, v62
	v_mul_f32_e32 v250, v64, v250
	v_mul_f32_e32 v59, v62, v59
	v_mul_f32_e32 v60, v250, v60
	v_mul_f32_e32 v62, 0xbfb8aa3b, v65
	v_exp_f32_e32 v62, v62
	s_nop 0
	v_add_f32_e32 v62, 1.0, v62
	v_rcp_f32_e32 v62, v62
	s_nop 0
	v_mul_f32_e32 v62, v65, v62
	v_mul_f32_e32 v61, v62, v61
	v_mul_f32_e32 v62, 0xbfb8aa3b, v54
	v_mul_f32_e32 v250, 0xbfb8aa3b, v55
	v_exp_f32_e32 v62, v62
	v_exp_f32_e32 v250, v250
	v_add_f32_e32 v62, 1.0, v62
	v_add_f32_e32 v250, 1.0, v250
	v_rcp_f32_e32 v62, v62
	v_rcp_f32_e32 v250, v250
	v_mul_f32_e32 v54, v54, v62
	v_mul_f32_e32 v250, v55, v250
	v_mul_f32_e32 v62, v54, v50
	v_mul_f32_e32 v63, v250, v51
	v_mul_f32_e32 v50, 0xbfb8aa3b, v56
	v_exp_f32_e32 v50, v50
	v_lshl_add_u64 v[54:55], v[66:67], 0, v[114:115]
	v_add_f32_e32 v50, 1.0, v50
	v_rcp_f32_e32 v50, v50
	s_nop 0
	v_mul_f32_e32 v50, v56, v50
	v_mul_f32_e32 v56, v50, v52
	v_mul_f32_e32 v50, 0xbfb8aa3b, v57
	v_exp_f32_e32 v50, v50
	s_nop 0
	v_add_f32_e32 v50, 1.0, v50
	v_rcp_f32_e32 v50, v50
	s_nop 0
	v_mul_f32_e32 v50, v57, v50
	v_mul_f32_e32 v53, v50, v53
	v_cvt_pk_bf16_f32 v50, v58, v59
	v_cvt_pk_bf16_f32 v51, v60, v61
	v_cvt_pk_bf16_f32 v52, v62, v63
	v_cvt_pk_bf16_f32 v53, v56, v53
	global_store_dwordx4 v[54:55], v[50:53], off
	s_nop 1
	v_mul_f32_e32 v52, 0xbfb8aa3b, v46
	v_exp_f32_e32 v52, v52
	v_add_u32_e32 v50, 0x90, v146
	v_mad_i64_i32 v[50:51], s[18:19], v50, s89, v[140:141]
	v_add_f32_e32 v52, 1.0, v52
	v_rcp_f32_e32 v52, v52
	s_nop 0
	v_mul_f32_e32 v46, v46, v52
	v_mul_f32_e32 v42, v46, v42
	v_mul_f32_e32 v46, 0xbfb8aa3b, v47
	v_mul_f32_e32 v250, 0xbfb8aa3b, v48
	v_exp_f32_e32 v46, v46
	v_exp_f32_e32 v250, v250
	v_add_f32_e32 v46, 1.0, v46
	v_add_f32_e32 v250, 1.0, v250
	v_rcp_f32_e32 v46, v46
	v_rcp_f32_e32 v250, v250
	v_mul_f32_e32 v46, v47, v46
	v_mul_f32_e32 v250, v48, v250
	v_mul_f32_e32 v43, v46, v43
	v_mul_f32_e32 v44, v250, v44
	v_mul_f32_e32 v46, 0xbfb8aa3b, v49
	v_exp_f32_e32 v46, v46
	s_nop 0
	v_add_f32_e32 v46, 1.0, v46
	v_rcp_f32_e32 v46, v46
	s_nop 0
	v_mul_f32_e32 v46, v49, v46
	v_mul_f32_e32 v45, v46, v45
	v_mul_f32_e32 v46, 0xbfb8aa3b, v38
	v_mul_f32_e32 v250, 0xbfb8aa3b, v39
; __device__ __forceinline__ unsigned cvt_pk_bf16(float lo, float hi) { unsigned r; asm volatile("v_cvt_pk_bf16_f32 %0, %1, %2" : "=v"(r) : "v"(lo), "v"(hi)); return r; }
; __device__ __forceinline__ float sigmoid_f(float x) { return __builtin_amdgcn_rcpf(1.0f + __builtin_amdgcn_exp2f(-1.4426950408889634f * x)); }
; #define PG8_BAR __builtin_amdgcn_s_barrier()
;     __device__ __forceinline__ void operator()(const f32x4 (&acc)[2][2][4][2], const Unit& u, int wr, int wc, int fr, int fq) const {
;         const int row0 = u.pm * BM + wr * 64 + fr, col0 = u.pn * HALF + wc * 32 + 8 * fq;
; #pragma unroll
;         for (int ai = 0; ai < 2; ++ai)
; #pragma unroll
;             for (int m = 0; m < 4; ++m) {
;                 bf16_t* rowp = O + (size_t)(row0 + ai * HALF + m * 16) * ldc + col0;
;                 float v[8];
; #pragma unroll
;                 for (int n = 0; n < 2; ++n)
; #pragma unroll
;                     for (int e = 0; e < 4; ++e) { const float g = acc[ai][0][m][n][e], up = acc[ai][1][m][n][e]; v[4 * n + e] = g * sigmoid_f(g) * up; }
;                 u32x4 w; w.x = cvt_pk_bf16(v[0], v[1]); w.y = cvt_pk_bf16(v[2], v[3]); w.z = cvt_pk_bf16(v[4], v[5]); w.w = cvt_pk_bf16(v[6], v[7]);
;                 *(u32x4*)rowp = w;
;             }
; template <class Epi, class Sched, bool ALIGN_EPI = false, bool SP2 = false>
; __device__ __forceinline__ void gemm_phase(PG8_LAS unsigned char* lds, const Gemm g, const Sched& S, const Epi& E) {
;     ...
;         if constexpr (ALIGN_EPI) { if (wr == 0) PG8_BAR; }
;         if constexpr (!Epi::AFTER_DRAIN) { E(acc, cur, wr, wc, fr, fq); S.done(cur); }
;         if (!has_next) break;
; #pragma unroll
;         for (int a = 0; a < 2; ++a)
; #pragma unroll
;             for (int b = 0; b < 2; ++b)
; #pragma unroll
;                 for (int m = 0; m < 4; ++m)
; #pragma unroll
;                     for (int n = 0; n < 2; ++n) acc[a][b][m][n] = (f32x4){0.f, 0.f, 0.f, 0.f};
;         cur = nxt; cA = nA; cB = nB; ++ui;
;         if constexpr (ALIGN_EPI) { if (wr == 1) PG8_BAR; }
	v_exp_f32_e32 v46, v46
	v_exp_f32_e32 v250, v250
	v_add_f32_e32 v46, 1.0, v46
	v_add_f32_e32 v250, 1.0, v250
	v_rcp_f32_e32 v46, v46
	v_rcp_f32_e32 v250, v250
	v_mul_f32_e32 v38, v38, v46
	v_mul_f32_e32 v250, v39, v250
	v_mul_f32_e32 v46, v38, v34
	v_mul_f32_e32 v47, v250, v35
	v_mul_f32_e32 v34, 0xbfb8aa3b, v40
	v_exp_f32_e32 v34, v34
	v_lshl_add_u64 v[38:39], v[50:51], 0, v[114:115]
	v_add_f32_e32 v34, 1.0, v34
	v_rcp_f32_e32 v34, v34
	s_nop 0
	v_mul_f32_e32 v34, v40, v34
	v_mul_f32_e32 v40, v34, v36
	v_mul_f32_e32 v34, 0xbfb8aa3b, v41
	v_exp_f32_e32 v34, v34
	s_nop 0
	v_add_f32_e32 v34, 1.0, v34
	v_rcp_f32_e32 v34, v34
	s_nop 0
	v_mul_f32_e32 v34, v41, v34
	v_mul_f32_e32 v37, v34, v37
	v_cvt_pk_bf16_f32 v34, v42, v43
	v_cvt_pk_bf16_f32 v35, v44, v45
	v_cvt_pk_bf16_f32 v36, v46, v47
	v_cvt_pk_bf16_f32 v37, v40, v37
	global_store_dwordx4 v[38:39], v[34:37], off
	s_nop 1
	v_mul_f32_e32 v36, 0xbfb8aa3b, v30
	v_exp_f32_e32 v36, v36
	v_add_u32_e32 v34, 0xa0, v146
	v_mad_i64_i32 v[34:35], s[18:19], v34, s89, v[140:141]
	v_add_f32_e32 v36, 1.0, v36
	v_rcp_f32_e32 v36, v36
	s_nop 0
	v_mul_f32_e32 v30, v30, v36
	v_mul_f32_e32 v26, v30, v26
	v_mul_f32_e32 v30, 0xbfb8aa3b, v31
	v_mul_f32_e32 v250, 0xbfb8aa3b, v32
	v_exp_f32_e32 v30, v30
	v_exp_f32_e32 v250, v250
	v_add_f32_e32 v30, 1.0, v30
	v_add_f32_e32 v250, 1.0, v250
	v_rcp_f32_e32 v30, v30
	v_rcp_f32_e32 v250, v250
	v_mul_f32_e32 v30, v31, v30
	v_mul_f32_e32 v250, v32, v250
	v_mul_f32_e32 v27, v30, v27
	v_mul_f32_e32 v28, v250, v28
	v_mul_f32_e32 v30, 0xbfb8aa3b, v33
	v_exp_f32_e32 v30, v30
	s_nop 0
	v_add_f32_e32 v30, 1.0, v30
	v_rcp_f32_e32 v30, v30
	s_nop 0
	v_mul_f32_e32 v30, v33, v30
	v_mul_f32_e32 v29, v30, v29
	v_mul_f32_e32 v30, 0xbfb8aa3b, v22
	v_mul_f32_e32 v250, 0xbfb8aa3b, v23
	v_exp_f32_e32 v30, v30
	v_exp_f32_e32 v250, v250
	v_add_f32_e32 v30, 1.0, v30
	v_add_f32_e32 v250, 1.0, v250
	v_rcp_f32_e32 v30, v30
	v_rcp_f32_e32 v250, v250
	v_mul_f32_e32 v22, v22, v30
	v_mul_f32_e32 v250, v23, v250
	v_mul_f32_e32 v30, v22, v18
	v_mul_f32_e32 v31, v250, v19
	v_mul_f32_e32 v18, 0xbfb8aa3b, v24
	v_exp_f32_e32 v18, v18
	v_lshl_add_u64 v[22:23], v[34:35], 0, v[114:115]
	v_add_f32_e32 v18, 1.0, v18
	v_rcp_f32_e32 v18, v18
	s_nop 0
	v_mul_f32_e32 v18, v24, v18
	v_mul_f32_e32 v24, v18, v20
	v_mul_f32_e32 v18, 0xbfb8aa3b, v25
	v_exp_f32_e32 v18, v18
	s_nop 0
	v_add_f32_e32 v18, 1.0, v18
	v_rcp_f32_e32 v18, v18
	s_nop 0
	v_mul_f32_e32 v18, v25, v18
	v_mul_f32_e32 v21, v18, v21
	v_cvt_pk_bf16_f32 v18, v26, v27
	v_cvt_pk_bf16_f32 v19, v28, v29
	v_cvt_pk_bf16_f32 v20, v30, v31
	v_cvt_pk_bf16_f32 v21, v24, v21
	global_store_dwordx4 v[22:23], v[18:21], off
	s_nop 1
	v_mul_f32_e32 v20, 0xbfb8aa3b, v14
	v_exp_f32_e32 v20, v20
	v_add_u32_e32 v18, 0xb0, v146
	v_mad_i64_i32 v[18:19], s[18:19], v18, s89, v[140:141]
	v_add_f32_e32 v20, 1.0, v20
	v_rcp_f32_e32 v20, v20
	s_nop 0
	v_mul_f32_e32 v14, v14, v20
	v_mul_f32_e32 v10, v14, v10
	v_mul_f32_e32 v14, 0xbfb8aa3b, v15
	v_mul_f32_e32 v250, 0xbfb8aa3b, v16
	v_exp_f32_e32 v14, v14
	v_exp_f32_e32 v250, v250
	v_add_f32_e32 v14, 1.0, v14
	v_add_f32_e32 v250, 1.0, v250
	v_rcp_f32_e32 v14, v14
	v_rcp_f32_e32 v250, v250
	v_mul_f32_e32 v14, v15, v14
	v_mul_f32_e32 v250, v16, v250
	v_mul_f32_e32 v11, v14, v11
	v_mul_f32_e32 v12, v250, v12
	v_mul_f32_e32 v14, 0xbfb8aa3b, v17
	v_exp_f32_e32 v14, v14
	s_nop 0
	v_add_f32_e32 v14, 1.0, v14
	v_rcp_f32_e32 v14, v14
	s_nop 0
	v_mul_f32_e32 v14, v17, v14
	v_mul_f32_e32 v13, v14, v13
	v_mul_f32_e32 v14, 0xbfb8aa3b, v6
	v_mul_f32_e32 v250, 0xbfb8aa3b, v7
	v_exp_f32_e32 v14, v14
	v_exp_f32_e32 v250, v250
	v_add_f32_e32 v14, 1.0, v14
	v_add_f32_e32 v250, 1.0, v250
	v_rcp_f32_e32 v14, v14
	v_rcp_f32_e32 v250, v250
	v_mul_f32_e32 v6, v6, v14
	v_mul_f32_e32 v250, v7, v250
	v_mul_f32_e32 v14, v6, v2
	v_mul_f32_e32 v15, v250, v3
	v_mul_f32_e32 v2, 0xbfb8aa3b, v8
	v_exp_f32_e32 v2, v2
	v_lshl_add_u64 v[6:7], v[18:19], 0, v[114:115]
	v_add_f32_e32 v2, 1.0, v2
	v_rcp_f32_e32 v2, v2
	s_nop 0
	v_mul_f32_e32 v2, v8, v2
	v_mul_f32_e32 v8, v2, v4
	v_mul_f32_e32 v2, 0xbfb8aa3b, v9
	v_exp_f32_e32 v2, v2
	s_nop 0
	v_add_f32_e32 v2, 1.0, v2
	v_rcp_f32_e32 v2, v2
	s_nop 0
	v_mul_f32_e32 v2, v9, v2
	v_mul_f32_e32 v5, v2, v5
	v_cvt_pk_bf16_f32 v2, v10, v11
	v_cvt_pk_bf16_f32 v3, v12, v13
	v_cvt_pk_bf16_f32 v4, v14, v15
	v_cvt_pk_bf16_f32 v5, v8, v5
	global_store_dwordx4 v[6:7], v[2:5], off
	s_cbranch_vccnz .LBB0_504
	s_andn2_b64 vcc, exec, s[8:9]
	s_cbranch_vccnz .LBB0_503
	s_barrier
	s_branch .LBB0_503
